# LN1 and LN2 row loops: two rows prefetched ahead into alternating register buffers (parity-selected), on top of v27
# speedup vs baseline: 1.0049x; 1.0049x over previous
.LBB0_15:
	v_readlane_b32 s14, v255, 3
	v_readlane_b32 s15, v255, 4
	v_mov_b32_e32 v0, v254
	s_andn2_b64 vcc, exec, s[14:15]
	s_cbranch_vccnz .LBB0_49
	s_load_dwordx2 s[20:21], s[10:11], 0x118
	v_and_b32_e32 v3, 63, v0
	v_ashrrev_i32_e32 v0, 6, v0
	v_readlane_b32 s2, v255, 23
	v_mov_b32_e32 v33, v149
	v_lshlrev_b32_e32 v148, 4, v3
	v_add_u32_e32 v32, s2, v0
	v_lshlrev_b64 v[0:1], 12, v[32:33]
	s_waitcnt lgkmcnt(0)
	v_lshl_add_u64 v[0:1], s[20:21], 0, v[0:1]
	v_lshl_add_u64 v[0:1], v[0:1], 0, v[148:149]
	global_load_dwordx4 v[16:19], v[0:1], off offset:3072
	global_load_dwordx4 v[20:23], v[0:1], off offset:2048
	global_load_dwordx4 v[24:27], v[0:1], off offset:1024
	global_load_dwordx4 v[28:31], v[0:1], off
	s_lshl_b32 s26, s82, 10
	s_lshl_b64 s[14:15], s[26:27], 2
	s_add_u32 s8, s8, s14
	s_addc_u32 s9, s9, s15
	s_add_u32 s14, s22, s14
	s_addc_u32 s15, s23, s15
	s_cmp_eq_u64 s[12:13], 0
	s_cselect_b64 s[22:23], -1, 0
	s_cmp_lg_u64 s[12:13], 0
	s_cselect_b64 s[16:17], -1, 0
	v_cmp_eq_u32_e32 vcc, 0, v3
	s_and_b64 s[28:29], s[16:17], vcc
	v_lshlrev_b32_e32 v0, 2, v3
	s_cmp_lg_u64 s[6:7], 0
	v_or_b32_e32 v2, 0x100, v0
	v_or_b32_e32 v4, 0x200, v0
	v_or_b32_e32 v6, 0x300, v0
	s_cselect_b64 s[30:31], -1, 0
	v_xor_b32_e32 v62, 64, v0
	v_xor_b32_e32 v63, 0x80, v0
	v_lshl_add_u64 v[34:35], s[8:9], 0, v[148:149]
	v_lshl_add_u64 v[36:37], s[14:15], 0, v[148:149]
	v_cndmask_b32_e64 v64, 0, 1, s[22:23]
	v_mov_b64_e32 v[38:39], s[6:7]
	v_cndmask_b32_e64 v65, 0, 1, s[30:31]
	global_load_dwordx4 v[80:83], v[34:35], off
	global_load_dwordx4 v[84:87], v[34:35], off offset:1024
	global_load_dwordx4 v[88:91], v[34:35], off offset:2048
	global_load_dwordx4 v[92:95], v[34:35], off offset:3072
	global_load_dwordx4 v[96:99], v[36:37], off
	global_load_dwordx4 v[100:103], v[36:37], off offset:1024
	global_load_dwordx4 v[104:107], v[36:37], off offset:2048
	global_load_dwordx4 v[108:111], v[36:37], off offset:3072
	v_and_b32_e32 v74, 31, v3
	v_lshlrev_b32_e32 v74, 7, v74
	v_sub_u32_e32 v74, v74, v148
	v_ashrrev_i32_e32 v75, 31, v74
	s_waitcnt vmcnt(0)
	v_readlane_b32 s6, v255, 5
	v_readlane_b32 s7, v255, 6
	v_lshlrev_b64 v[176:177], 12, v[32:33]
	v_lshl_add_u64 v[176:177], s[20:21], 0, v[176:177]
	v_lshl_add_u64 v[176:177], v[176:177], 0, s[6:7]
	v_lshl_add_u64 v[176:177], v[176:177], 0, v[148:149]
	global_load_dwordx4 v[160:163], v[176:177], off
	global_load_dwordx4 v[164:167], v[176:177], off offset:1024
	global_load_dwordx4 v[168:171], v[176:177], off offset:2048
	global_load_dwordx4 v[172:175], v[176:177], off offset:3072
	v_lshlrev_b32_e32 v40, 2, v2
	v_lshlrev_b32_e32 v42, 2, v4
	v_lshlrev_b32_e32 v44, 2, v6
	v_lshlrev_b32_e32 v148, 2, v0
	v_lshlrev_b32_e32 v46, 1, v0
	v_readlane_b32 s2, v255, 0
	s_and_b64 s[14:15], s[30:31], s[16:17]
	s_cbranch_scc1 .Lln2A_top
	s_or_b64 s[14:15], s[30:31], s[16:17]
	s_cbranch_scc0 .Lln2B_top
	s_branch .LBB0_24
.Lln2A_top:
	s_add_i32 s2, s2, s18
	v_ashrrev_i32_e32 v33, 31, v32
	s_cmpk_gt_i32 s2, 0x17ff
	v_lshlrev_b64 v[178:179], 12, v[32:33]
	s_cselect_b64 s[36:37], -1, 0
	v_lshl_add_u64 v[48:49], s[20:21], 0, v[178:179]
	v_add_u32_e32 v64, 0xffffe000, v32
	v_lshrrev_b32_e32 v64, 11, v64
	v_add_u32_e32 v64, 1, v64
	v_cmp_lt_i32_e32 vcc, s34, v32
	s_nop 1
	v_cndmask_b32_e32 v66, 0, v64, vcc
	v_mad_u64_u32 v[64:65], s[14:15], v66, s35, v[38:39]
	s_mov_b64 s[14:15], 0x1000
	s_nop 0
	v_lshl_add_u64 v[68:69], v[64:65], 0, s[14:15]
	v_mov_b32_e32 v41, v149
	v_mov_b32_e32 v43, v149
	v_mov_b32_e32 v45, v149
	v_lshl_add_u64 v[64:65], v[64:65], 0, v[148:149]
	v_lshl_add_u64 v[70:71], v[68:69], 0, v[148:149]
	global_load_dwordx4 v[112:115], v[70:71], off
	v_lshl_add_u64 v[70:71], v[68:69], 0, v[40:41]
	global_load_dwordx4 v[116:119], v[70:71], off
	v_lshl_add_u64 v[70:71], v[68:69], 0, v[42:43]
	global_load_dwordx4 v[120:123], v[70:71], off
	v_lshl_add_u64 v[70:71], v[68:69], 0, v[44:45]
	global_load_dwordx4 v[124:127], v[70:71], off
	global_load_dwordx4 v[128:131], v[64:65], off
	global_load_dwordx4 v[132:135], v[64:65], off offset:1024
	global_load_dwordx4 v[136:139], v[64:65], off offset:2048
	global_load_dwordx4 v[140:143], v[64:65], off offset:3072
	s_add_i32 s14, s2, s18
	s_cmpk_gt_i32 s14, 0x17ff
	s_cbranch_scc1 .Lln2A_nopf
	v_readlane_b32 s6, v255, 5
	v_readlane_b32 s7, v255, 6
	s_nop 1
	v_lshl_add_u64 v[178:179], v[48:49], 0, s[6:7]
	v_lshl_add_u64 v[178:179], v[178:179], 0, s[6:7]
	s_bitcmp1_b32 s2, 9
	s_cbranch_scc0 .Lln2A_pfB
	v_lshl_add_u64 v[12:13], v[178:179], 0, v[148:149]
	v_lshl_add_u64 v[70:71], v[12:13], 0, v[74:75]
	global_load_dwordx4 v[0:3], v[12:13], off
	global_load_dwordx4 v[4:7], v[12:13], off offset:1024
	global_load_dwordx4 v[8:11], v[12:13], off offset:2048
	s_nop 0
	global_load_dwordx4 v[12:15], v[12:13], off offset:3072
	s_branch .Lln2A_pfD
.Lln2A_pfB:
	v_lshl_add_u64 v[176:177], v[178:179], 0, v[148:149]
	v_lshl_add_u64 v[70:71], v[176:177], 0, v[74:75]
	global_load_dwordx4 v[160:163], v[176:177], off
	global_load_dwordx4 v[164:167], v[176:177], off offset:1024
	global_load_dwordx4 v[168:171], v[176:177], off offset:2048
	global_load_dwordx4 v[172:175], v[176:177], off offset:3072
.Lln2A_pfD:
	s_add_i32 s14, s14, s18
	s_cmpk_gt_i32 s14, 0x17ff
	s_cselect_b32 s14, 0, s6
	s_cselect_b32 s15, 0, s7
	v_lshl_add_u64 v[70:71], v[70:71], 0, s[14:15]
	global_load_dword v150, v[70:71], off

.Lln2A_28:
	s_or_b64 exec, exec, s[6:7]
	s_add_i32 s14, s2, s18
	s_cmpk_gt_i32 s14, 0x17ff
	s_cselect_b64 vcc, -1, 0
	s_load_dwordx2 s[14:15], s[10:11], 0x120
	s_cbranch_vccnz .Lln2A_wl
	s_waitcnt vmcnt(6)
	s_branch .Lln2A_wd

.Lln2A_wd:
	v_mov_b32_e32 v27, v26
	v_lshlrev_b64 v[76:77], 10, v[32:33]
	v_mov_b32_e32 v47, v149
	s_waitcnt lgkmcnt(0)
	v_lshl_add_u64 v[76:77], v[76:77], 1, s[14:15]
	s_mov_b64 s[14:15], 0xe0c1000
	v_lshl_add_u64 v[76:77], v[76:77], 0, v[46:47]
	v_lshl_add_u64 v[76:77], v[76:77], 0, s[14:15]
	v_pk_mul_f32 v[64:65], v[58:59], v[26:27]
	v_pk_mul_f32 v[66:67], v[28:29], v[26:27]
	v_pk_add_f32 v[68:69], v[112:113], 1.0 op_sel_hi:[1,0]
	v_pk_add_f32 v[70:71], v[114:115], 1.0 op_sel_hi:[1,0]
	v_pk_fma_f32 v[64:65], v[64:65], v[80:81], v[96:97]
	v_pk_fma_f32 v[66:67], v[66:67], v[82:83], v[98:99]
	v_pk_fma_f32 v[64:65], v[64:65], v[68:69], v[128:129]
	v_pk_fma_f32 v[66:67], v[66:67], v[70:71], v[130:131]
	v_cvt_pk_bf16_f32 v72, v64, v65
	v_cvt_pk_bf16_f32 v73, v66, v67
	global_store_dwordx2 v[76:77], v[72:73], off
	v_pk_mul_f32 v[64:65], v[54:55], v[26:27]
	v_pk_mul_f32 v[66:67], v[56:57], v[26:27]
	v_pk_add_f32 v[68:69], v[116:117], 1.0 op_sel_hi:[1,0]
	v_pk_add_f32 v[70:71], v[118:119], 1.0 op_sel_hi:[1,0]
	v_pk_fma_f32 v[64:65], v[64:65], v[84:85], v[100:101]
	v_pk_fma_f32 v[66:67], v[66:67], v[86:87], v[102:103]
	v_pk_fma_f32 v[64:65], v[64:65], v[68:69], v[132:133]
	v_pk_fma_f32 v[66:67], v[66:67], v[70:71], v[134:135]
	v_cvt_pk_bf16_f32 v72, v64, v65
	v_cvt_pk_bf16_f32 v73, v66, v67
	global_store_dwordx2 v[76:77], v[72:73], off offset:512
	v_pk_mul_f32 v[64:65], v[52:53], v[26:27]
	v_pk_mul_f32 v[66:67], v[50:51], v[26:27]
	v_pk_add_f32 v[68:69], v[120:121], 1.0 op_sel_hi:[1,0]
	v_pk_add_f32 v[70:71], v[122:123], 1.0 op_sel_hi:[1,0]
	v_pk_fma_f32 v[64:65], v[64:65], v[88:89], v[104:105]
	v_pk_fma_f32 v[66:67], v[66:67], v[90:91], v[106:107]
	v_pk_fma_f32 v[64:65], v[64:65], v[68:69], v[136:137]
	v_pk_fma_f32 v[66:67], v[66:67], v[70:71], v[138:139]
	v_cvt_pk_bf16_f32 v72, v64, v65
	v_cvt_pk_bf16_f32 v73, v66, v67
	global_store_dwordx2 v[76:77], v[72:73], off offset:1024
	v_pk_mul_f32 v[64:65], v[22:23], v[26:27]
	v_pk_mul_f32 v[66:67], v[20:21], v[26:27]
	v_pk_add_f32 v[68:69], v[124:125], 1.0 op_sel_hi:[1,0]
	v_pk_add_f32 v[70:71], v[126:127], 1.0 op_sel_hi:[1,0]
	v_pk_fma_f32 v[64:65], v[64:65], v[92:93], v[108:109]
	v_pk_fma_f32 v[66:67], v[66:67], v[94:95], v[110:111]
	v_pk_fma_f32 v[64:65], v[64:65], v[68:69], v[140:141]
	v_pk_fma_f32 v[66:67], v[66:67], v[70:71], v[142:143]
	v_cvt_pk_bf16_f32 v72, v64, v65
	v_cvt_pk_bf16_f32 v73, v66, v67
	global_store_dwordx2 v[76:77], v[72:73], off offset:1536
	v_add_u32_e32 v32, s90, v32
	s_and_b64 vcc, exec, s[36:37]
	s_cbranch_vccnz .LBB0_49
	s_bitcmp1_b32 s2, 9
	s_cbranch_scc0 .Lln2A_cpA
	v_mov_b64_e32 v[18:19], v[174:175]
	v_mov_b64_e32 v[16:17], v[172:173]
	v_mov_b64_e32 v[22:23], v[170:171]
	v_mov_b64_e32 v[20:21], v[168:169]
	v_mov_b64_e32 v[26:27], v[166:167]
	v_mov_b64_e32 v[24:25], v[164:165]
	v_mov_b64_e32 v[30:31], v[162:163]
	v_mov_b64_e32 v[28:29], v[160:161]
	s_branch .Lln2A_top
.Lln2A_cpA:
	v_mov_b64_e32 v[18:19], v[14:15]
	v_mov_b64_e32 v[16:17], v[12:13]
	v_mov_b64_e32 v[22:23], v[10:11]
	v_mov_b64_e32 v[20:21], v[8:9]
	v_mov_b64_e32 v[26:27], v[6:7]
	v_mov_b64_e32 v[24:25], v[4:5]
	v_mov_b64_e32 v[30:31], v[2:3]
	v_mov_b64_e32 v[28:29], v[0:1]
	s_branch .Lln2A_top
.Lln2B_top:
	s_add_i32 s2, s2, s18
	v_ashrrev_i32_e32 v33, 31, v32
	s_cmpk_gt_i32 s2, 0x17ff
	v_lshlrev_b64 v[178:179], 12, v[32:33]
	s_cselect_b64 s[36:37], -1, 0
	v_lshl_add_u64 v[48:49], s[20:21], 0, v[178:179]
	s_add_i32 s14, s2, s18
	s_cmpk_gt_i32 s14, 0x17ff
	s_cbranch_scc1 .Lln2B_nopf
	v_readlane_b32 s6, v255, 5
	v_readlane_b32 s7, v255, 6
	s_nop 1
	v_lshl_add_u64 v[178:179], v[48:49], 0, s[6:7]
	v_lshl_add_u64 v[178:179], v[178:179], 0, s[6:7]
	s_bitcmp1_b32 s2, 9
	s_cbranch_scc0 .Lln2B_pfB
	v_lshl_add_u64 v[12:13], v[178:179], 0, v[148:149]
	v_lshl_add_u64 v[70:71], v[12:13], 0, v[74:75]
	global_load_dwordx4 v[0:3], v[12:13], off
	global_load_dwordx4 v[4:7], v[12:13], off offset:1024
	global_load_dwordx4 v[8:11], v[12:13], off offset:2048
	s_nop 0
	global_load_dwordx4 v[12:15], v[12:13], off offset:3072
	s_branch .Lln2B_pfD

.Lln2B_28:
	s_or_b64 exec, exec, s[6:7]
	v_mov_b32_e32 v27, v26
	v_lshl_add_u64 v[68:69], v[48:49], 0, v[148:149]
	v_pk_mul_f32 v[64:65], v[58:59], v[26:27]
	v_pk_mul_f32 v[66:67], v[28:29], v[26:27]
	v_pk_fma_f32 v[64:65], v[64:65], v[80:81], v[96:97]
	v_pk_fma_f32 v[66:67], v[66:67], v[82:83], v[98:99]
	global_store_dwordx4 v[68:69], v[64:67], off
	v_pk_mul_f32 v[112:113], v[54:55], v[26:27]
	v_pk_mul_f32 v[114:115], v[56:57], v[26:27]
	v_pk_fma_f32 v[112:113], v[112:113], v[84:85], v[100:101]
	v_pk_fma_f32 v[114:115], v[114:115], v[86:87], v[102:103]
	global_store_dwordx4 v[68:69], v[112:115], off offset:1024
	v_pk_mul_f32 v[116:117], v[52:53], v[26:27]
	v_pk_mul_f32 v[118:119], v[50:51], v[26:27]
	v_pk_fma_f32 v[116:117], v[116:117], v[88:89], v[104:105]
	v_pk_fma_f32 v[118:119], v[118:119], v[90:91], v[106:107]
	global_store_dwordx4 v[68:69], v[116:119], off offset:2048
	v_pk_mul_f32 v[120:121], v[22:23], v[26:27]
	v_pk_mul_f32 v[122:123], v[20:21], v[26:27]
	v_pk_fma_f32 v[120:121], v[120:121], v[92:93], v[108:109]
	v_pk_fma_f32 v[122:123], v[122:123], v[94:95], v[110:111]
	global_store_dwordx4 v[68:69], v[120:123], off offset:3072
	v_add_u32_e32 v32, s90, v32
	s_and_b64 vcc, exec, s[36:37]
	s_cbranch_vccnz .LBB0_49
	s_add_i32 s14, s2, s18
	s_cmpk_gt_i32 s14, 0x17ff
	s_cbranch_scc1 .Lln2B_bw
	s_waitcnt vmcnt(9)
	s_branch .Lln2B_bd
.Lln2B_bw:
	s_waitcnt vmcnt(4)
.Lln2B_bd:
	s_bitcmp1_b32 s2, 9
	s_cbranch_scc0 .Lln2B_cpA
	v_mov_b64_e32 v[18:19], v[174:175]
	v_mov_b64_e32 v[16:17], v[172:173]
	v_mov_b64_e32 v[22:23], v[170:171]
	v_mov_b64_e32 v[20:21], v[168:169]
	v_mov_b64_e32 v[26:27], v[166:167]
	v_mov_b64_e32 v[24:25], v[164:165]
	v_mov_b64_e32 v[30:31], v[162:163]
	v_mov_b64_e32 v[28:29], v[160:161]
	s_branch .Lln2B_top

.LBB0_201:
	v_readlane_b32 s14, v255, 3
	v_readlane_b32 s15, v255, 4
	s_mov_b64 s[6:7], s[0:1]
	s_mov_b64 s[4:5], s[0:1]
	s_waitcnt lgkmcnt(0)
	s_mov_b64 s[8:9], s[0:1]
	s_mov_b64 s[10:11], s[0:1]
	s_mov_b64 s[12:13], s[0:1]
	v_mov_b32_e32 v0, v254
	s_andn2_b64 vcc, exec, s[14:15]
	s_cbranch_vccnz .LBB0_210
	s_load_dwordx2 s[14:15], s[6:7], 0x118
	v_and_b32_e32 v5, 63, v0
	v_ashrrev_i32_e32 v0, 6, v0
	v_readlane_b32 s2, v255, 23
	v_lshlrev_b32_e32 v2, 4, v5
	v_mov_b32_e32 v3, v149
	v_add_u32_e32 v148, s2, v0
	v_lshlrev_b64 v[0:1], 12, v[148:149]
	s_waitcnt lgkmcnt(0)
	v_lshl_add_u64 v[0:1], s[14:15], 0, v[0:1]
	v_lshl_add_u64 v[0:1], v[0:1], 0, v[2:3]
	global_load_dwordx4 v[16:19], v[0:1], off offset:3072
	global_load_dwordx4 v[20:23], v[0:1], off offset:2048
	global_load_dwordx4 v[24:27], v[0:1], off offset:1024
	global_load_dwordx4 v[28:31], v[0:1], off
	s_load_dwordx2 s[4:5], s[4:5], 0xe8
	s_nop 0
	s_load_dwordx2 s[16:17], s[10:11], 0x120
	s_load_dwordx2 s[20:21], s[8:9], 0xf0
	s_nop 0
	s_load_dwordx2 s[10:11], s[12:13], 0x120
	s_mul_i32 s26, s82, 0xd800
	s_lshl_b64 s[8:9], s[26:27], 2
	s_waitcnt lgkmcnt(0)
	s_add_u32 s8, s16, s8
	s_addc_u32 s9, s17, s9
	s_add_u32 s10, s10, 0x110c1000
	s_addc_u32 s11, s11, 0
	s_lshl_b32 s26, s82, 10
	s_lshl_b64 s[12:13], s[26:27], 2
	s_add_u32 s20, s20, s12
	s_addc_u32 s21, s21, s13
	s_add_u32 s22, s4, s12
	s_addc_u32 s23, s5, s13
	s_cmp_lg_u64 s[16:17], 0
	v_readlane_b32 s16, v255, 5
	v_lshlrev_b32_e32 v32, 2, v5
	s_cselect_b64 s[12:13], -1, 0
	v_readlane_b32 s17, v255, 6
	s_add_u32 s14, s14, s16
	v_or_b32_e32 v0, 0x100, v32
	v_or_b32_e32 v4, 0x200, v32
	v_or_b32_e32 v6, 0x300, v32
	s_addc_u32 s15, s15, s17
	v_xor_b32_e32 v33, 64, v32
	v_xor_b32_e32 v60, 0x80, v32
	v_cmp_eq_u32_e64 s[4:5], 0, v5
	v_lshl_add_u64 v[34:35], s[22:23], 0, v[2:3]
	v_lshl_add_u64 v[36:37], s[20:21], 0, v[2:3]
	v_lshl_add_u64 v[38:39], s[14:15], 0, v[2:3]
	global_load_dwordx4 v[80:83], v[34:35], off
	global_load_dwordx4 v[84:87], v[34:35], off offset:1024
	global_load_dwordx4 v[88:91], v[34:35], off offset:2048
	global_load_dwordx4 v[92:95], v[34:35], off offset:3072
	global_load_dwordx4 v[96:99], v[36:37], off
	global_load_dwordx4 v[100:103], v[36:37], off offset:1024
	global_load_dwordx4 v[104:107], v[36:37], off offset:2048
	global_load_dwordx4 v[108:111], v[36:37], off offset:3072
	v_and_b32_e32 v74, 31, v5
	v_lshlrev_b32_e32 v74, 7, v74
	v_sub_u32_e32 v74, v74, v2
	v_ashrrev_i32_e32 v75, 31, v74
	v_lshl_add_u64 v[74:75], v[38:39], 0, v[74:75]
	s_waitcnt vmcnt(0)
	v_ashrrev_i32_e32 v47, 31, v148
	v_mov_b32_e32 v46, v148
	v_lshlrev_b64 v[48:49], 10, v[46:47]
	v_lshl_add_u64 v[176:177], v[48:49], 2, v[38:39]
	global_load_dwordx4 v[160:163], v[176:177], off
	global_load_dwordx4 v[164:167], v[176:177], off offset:1024
	global_load_dwordx4 v[168:171], v[176:177], off offset:2048
	global_load_dwordx4 v[172:175], v[176:177], off offset:3072
	v_lshlrev_b32_e32 v40, 2, v0
	v_lshlrev_b32_e32 v42, 2, v4
	v_lshlrev_b32_e32 v44, 2, v6
	v_mov_b32_e32 v46, v148
	v_readlane_b32 s2, v255, 0
	s_branch .LBB0_204
.LBB0_203:
	v_add_u32_e32 v46, s90, v46
	s_and_b64 vcc, exec, s[20:21]
	s_cbranch_vccnz .LBB0_210
	s_bitcmp1_b32 s2, 9
	s_cbranch_scc0 .Lln1_cpA
	v_mov_b64_e32 v[30:31], v[162:163]
	v_mov_b64_e32 v[28:29], v[160:161]
	v_mov_b64_e32 v[26:27], v[166:167]
	v_mov_b64_e32 v[24:25], v[164:165]
	v_mov_b64_e32 v[22:23], v[170:171]
	v_mov_b64_e32 v[20:21], v[168:169]
	v_mov_b64_e32 v[18:19], v[174:175]
	v_mov_b64_e32 v[16:17], v[172:173]
	s_branch .LBB0_204
.Lln1_cpA:
	v_mov_b64_e32 v[30:31], v[2:3]
	v_mov_b64_e32 v[28:29], v[0:1]
	v_mov_b64_e32 v[26:27], v[6:7]
	v_mov_b64_e32 v[24:25], v[4:5]
	v_mov_b64_e32 v[22:23], v[10:11]
	v_mov_b64_e32 v[20:21], v[8:9]
	v_mov_b64_e32 v[18:19], v[14:15]
	v_mov_b64_e32 v[16:17], v[12:13]
.LBB0_204:
	s_add_i32 s2, s2, s18
	s_cmpk_gt_i32 s2, 0x17ff
	v_ashrrev_i32_e32 v47, 31, v46
	s_cselect_b64 s[20:21], -1, 0
	v_lshlrev_b64 v[48:49], 10, v[46:47]
	v_add_u32_e32 v64, 0xffffe000, v46
	v_lshrrev_b32_e32 v64, 11, v64
	v_add_u32_e32 v64, 1, v64
	v_cmp_lt_i32_e32 vcc, s34, v46
	s_nop 1
	v_cndmask_b32_e32 v66, 0, v64, vcc
	v_mov_b64_e32 v[64:65], s[8:9]
	v_mad_u64_u32 v[64:65], s[14:15], v66, s35, v[64:65]
	s_mov_b64 s[14:15], 0x3000
	s_nop 0
	v_lshl_add_u64 v[66:67], v[64:65], 0, s[14:15]
	s_mov_b64 s[14:15], 0x4000
	v_lshl_add_u64 v[68:69], v[64:65], 0, s[14:15]
	v_lshlrev_b32_e32 v148, 2, v32
	v_mov_b32_e32 v41, v149
	v_mov_b32_e32 v43, v149
	v_mov_b32_e32 v45, v149
	v_lshl_add_u64 v[70:71], v[68:69], 0, v[148:149]
	global_load_dwordx4 v[112:115], v[70:71], off
	v_lshl_add_u64 v[70:71], v[68:69], 0, v[40:41]
	global_load_dwordx4 v[116:119], v[70:71], off
	v_lshl_add_u64 v[70:71], v[68:69], 0, v[42:43]
	global_load_dwordx4 v[120:123], v[70:71], off
	v_lshl_add_u64 v[70:71], v[68:69], 0, v[44:45]
	global_load_dwordx4 v[124:127], v[70:71], off
	v_lshl_add_u64 v[70:71], v[66:67], 0, v[148:149]
	global_load_dwordx4 v[128:131], v[70:71], off
	v_lshl_add_u64 v[70:71], v[66:67], 0, v[40:41]
	global_load_dwordx4 v[132:135], v[70:71], off
	v_lshl_add_u64 v[70:71], v[66:67], 0, v[42:43]
	global_load_dwordx4 v[136:139], v[70:71], off
	v_lshl_add_u64 v[70:71], v[66:67], 0, v[44:45]
	global_load_dwordx4 v[140:143], v[70:71], off
	s_add_i32 s14, s2, s18
	s_cmpk_gt_i32 s14, 0x17ff
	s_cbranch_scc1 .Lln1_nopf
	v_lshl_add_u64 v[70:71], v[48:49], 2, v[74:75]
	v_lshl_add_u64 v[70:71], v[70:71], 0, s[16:17]
	s_bitcmp1_b32 s2, 9
	s_cbranch_scc0 .Lln1_pfB
	v_lshl_add_u64 v[12:13], v[48:49], 2, v[38:39]
	v_lshl_add_u64 v[12:13], v[12:13], 0, s[16:17]
	global_load_dwordx4 v[0:3], v[12:13], off
	global_load_dwordx4 v[4:7], v[12:13], off offset:1024
	global_load_dwordx4 v[8:11], v[12:13], off offset:2048
	s_nop 0
	global_load_dwordx4 v[12:15], v[12:13], off offset:3072
	s_branch .Lln1_pfD
.Lln1_pfB:
	v_lshl_add_u64 v[176:177], v[48:49], 2, v[38:39]
	v_lshl_add_u64 v[176:177], v[176:177], 0, s[16:17]
	global_load_dwordx4 v[160:163], v[176:177], off
	global_load_dwordx4 v[164:167], v[176:177], off offset:1024
	global_load_dwordx4 v[168:171], v[176:177], off offset:2048
	global_load_dwordx4 v[172:175], v[176:177], off offset:3072
.Lln1_pfD:
	s_add_i32 s14, s14, s18
	s_cmpk_gt_i32 s14, 0x17ff
	s_cselect_b32 s14, 0, s16
	s_cselect_b32 s15, 0, s17
	v_lshl_add_u64 v[70:71], v[70:71], 0, s[14:15]
	global_load_dword v150, v[70:71], off

.LBB0_208:
	s_or_b64 exec, exec, s[14:15]
	s_load_dwordx2 s[14:15], s[6:7], 0x120
	s_add_i32 s2, s2, s18
	s_cmpk_gt_i32 s2, 0x17ff
	s_cselect_b64 vcc, -1, 0
	s_sub_i32 s2, s2, s18
	s_cbranch_vccnz .Lln1_wl
	s_waitcnt vmcnt(6)
	s_branch .Lln1_wd
